# recurrence: producer waves raised to s_setprio 3 for the loop (on the S=5 rebalanced stack)
# baseline (speedup 1.0000x reference)
; __device__ __forceinline__ float* karg_out() { return *(volatile KAS fptr_t*)((const KAS char*)__builtin_amdgcn_kernarg_segment_ptr() + 256); }
; __device__ __forceinline__ void delta_rec_task(const Params& P, LAS unsigned char* lds, int b, int h, int tid) {
;     ...
;         }
;     }
;     if (!producer) { float* So = karg_out() + O_SP + ((size_t)bh * 128 + 4 * hh) * 128 + 32 * wave + n;
.LBB0_1818:
	s_setprio 0
	s_or_b64 exec, exec, s[6:7]
	s_and_saveexec_b64 s[4:5], s[8:9]
	s_cbranch_execz .LBB0_1820

; __device__ __forceinline__ void delta_pre_load(int b, int h, int c, int pt, DeltaPre& dp) {
;     const int bh = b * 8 + h, tt = pt >> 3, d0 = (pt & 7) * 16; const size_t t = (size_t)bh * SEQ + c * 32 + tt;
;     const size_t ro = ((size_t)b * SEQ + c * 32 + tt) * D + h * 128 + d0;
;     const bf16* Kt = (const bf16*)(karg_ws() + WS_Z + 3 * ZB) + ro; const bf16* Qt = (const bf16*)(karg_ws() + WS_H) + ro; const bf16* Vt = (const bf16*)(karg_ws() + WS_Z + 4 * ZB) + ro;
;     dp.k0 = *(const u32x4*)Kt; dp.k1 = *(const u32x4*)(Kt + 8); dp.q0 = *(const u32x4*)Qt; dp.q1 = *(const u32x4*)(Qt + 8); dp.v0 = *(const u32x4*)Vt; dp.v1 = *(const u32x4*)(Vt + 8);
;     const float* GC = (const float*)(karg_ws() + WS_GC);
;     dp.gct = GC[t]; dp.gl = GC[(size_t)bh * SEQ + c * 32 + 31]; dp.bet = ((const float*)(karg_ws() + WS_BETA))[t];
;     dp.nk = ((const float*)((const unsigned char*)karg_out() + OSB_NK))[t]; dp.nq = ((const float*)((const unsigned char*)karg_out() + OSB_NQ))[t];
;     dp.tia = *(const u32x4*)((const bf16*)(karg_ws() + (pt < 128 ? WS_TINV : WS_ATT)) + ((size_t)bh * 64 + c) * 1024 + (pt & 127) * 8);
; }
; __device__ __forceinline__ void delta_rec_stage(LAS unsigned char* buf, int pt, const DeltaPre& dp) {
;     const int tt = pt >> 3, dg = pt & 7, d0 = dg * 16;
;     { LAS bf16* dst = (LAS bf16*)(buf + (pt < 128 ? DR_TI : DR_AT)) + ((pt & 127) >> 2) * 40 + (pt & 3) * 8; *(LAS u32x4*)dst = dp.tia; }
;     if (pt == 0) *(LAS float*)(buf + DR_EGL) = __expf(dp.gl);
;     const float eg = __expf(dp.gct), ekd = __expf(dp.gl - dp.gct);
; __device__ __forceinline__ void delta_rec_task(const Params& P, LAS unsigned char* lds, int b, int h, int tid) {
;     ...
;         const int pt = opq(tid) - 256;
;         float dn16[16];
; #pragma unroll
;         for (int e = 0; e < 16; ++e) dn16[e] = INP(25)[(pt & 7) * 16 + e];
;         bf16* zgp = (bf16*)(karg_ws() + WS_Z + 5 * ZB) + ((size_t)b * SEQ + (pt >> 3)) * D + h * 128 + (pt & 7) * 16;
;         u32x4 zc0 = {0u, 0u, 0u, 0u}, zc1 = zc0, zn0, zn1;
;     ...
;         for (int c = 0; c < NC; ++c) {
;             if (c > 0) { dcur = dnxt; zc0 = zn0; zc1 = zn1; }
;             if (c + 2 < NC) delta_pre_load(b, h, c + 2, pt, dnxt);
;             zn0 = *(const u32x4*)(zgp + (size_t)c * 32 * D); zn1 = *(const u32x4*)(zgp + (size_t)c * 32 * D + 8);
;             if (c + 1 < NC) delta_rec_stage(lds + ((c + 1) & 1) * DR_BUF, pt, dcur);
.LBB0_1835:
	s_load_dwordx2 s[44:45], s[0:1], 0x100
	s_setprio 3
	v_mov_b32_e32 v26, v113
	s_load_dwordx2 s[4:5], s[0:1], 0xc8
	v_lshlrev_b32_e32 v32, 4, v26
	v_and_b32_e32 v27, 0x70, v32
	v_lshlrev_b32_e32 v111, 2, v27
	s_ashr_i32 s13, s12, 31
	s_waitcnt lgkmcnt(0)
	global_load_dword v102, v111, s[4:5]
	s_load_dwordx2 s[4:5], s[0:1], 0xc8
	v_add_u32_e32 v33, 0xffffff00, v26
	v_ashrrev_i32_e32 v22, 3, v33
	v_ashrrev_i32_e32 v23, 31, v22
	s_mov_b64 s[10:11], 0x20000
	s_waitcnt lgkmcnt(0)
	global_load_dword v103, v111, s[4:5] offset:4
	s_load_dwordx2 s[4:5], s[0:1], 0xc8
	s_mov_b64 s[22:23], 0xb100000
	s_mov_b32 s21, 0xb100000
	s_mov_b64 s[24:25], 0x3000000
	s_mov_b32 s38, 0x3000000
	s_waitcnt lgkmcnt(0)
	global_load_dword v100, v111, s[4:5] offset:8
	s_load_dwordx2 s[4:5], s[0:1], 0xc8
	s_mov_b64 s[26:27], 0xd140000
	s_mov_b32 s39, 0xd140000
	v_mov_b32_e32 v21, 0
	v_lshlrev_b64 v[24:25], 11, v[22:23]
	s_waitcnt lgkmcnt(0)
	global_load_dword v101, v111, s[4:5] offset:12
	s_load_dwordx2 s[4:5], s[0:1], 0xc8
	v_lshlrev_b32_e32 v114, 1, v27
	v_mov_b32_e32 v115, v21
	v_mov_b32_e32 v34, 0x7600
	v_mov_b32_e32 v35, 0x6c00
	s_waitcnt lgkmcnt(0)
	global_load_dword v98, v111, s[4:5] offset:16
	s_load_dwordx2 s[4:5], s[0:1], 0xc8
	s_waitcnt lgkmcnt(0)
	global_load_dword v99, v111, s[4:5] offset:20
	s_load_dwordx2 s[4:5], s[0:1], 0xc8
	s_waitcnt lgkmcnt(0)
	global_load_dword v96, v111, s[4:5] offset:24
	s_load_dwordx2 s[4:5], s[0:1], 0xc8
	s_waitcnt lgkmcnt(0)
	global_load_dword v97, v111, s[4:5] offset:28
	s_load_dwordx2 s[4:5], s[0:1], 0xc8
	s_waitcnt lgkmcnt(0)
	global_load_dword v94, v111, s[4:5] offset:32
	s_load_dwordx2 s[4:5], s[0:1], 0xc8
	s_waitcnt lgkmcnt(0)
	global_load_dword v95, v111, s[4:5] offset:36
	s_load_dwordx2 s[4:5], s[0:1], 0xc8
	s_waitcnt lgkmcnt(0)
	global_load_dword v92, v111, s[4:5] offset:40
	s_load_dwordx2 s[4:5], s[0:1], 0xc8
	s_waitcnt lgkmcnt(0)
	global_load_dword v93, v111, s[4:5] offset:44
	s_load_dwordx2 s[4:5], s[0:1], 0xc8
	s_waitcnt lgkmcnt(0)
	global_load_dword v104, v111, s[4:5] offset:48
	s_load_dwordx2 s[4:5], s[0:1], 0xc8
	s_waitcnt lgkmcnt(0)
	global_load_dword v105, v111, s[4:5] offset:52
	s_load_dwordx2 s[4:5], s[0:1], 0xc8
	s_waitcnt lgkmcnt(0)
	global_load_dword v106, v111, s[4:5] offset:56
	s_load_dwordx2 s[14:15], s[0:1], 0xc8
	s_lshl_b64 s[4:5], s[12:13], 22
	s_waitcnt lgkmcnt(0)
	global_load_dword v107, v111, s[14:15] offset:60
	s_load_dwordx2 s[16:17], s[0:1], 0x108
	s_load_dwordx2 s[28:29], s[0:1], 0x108
	s_load_dwordx2 s[30:31], s[0:1], 0x108
	s_load_dwordx2 s[34:35], s[0:1], 0x108
	s_mov_b32 s15, 0
	s_waitcnt lgkmcnt(0)
	s_add_u32 s36, s16, s4
	s_addc_u32 s37, s17, s5
	s_lshl_b64 s[12:13], s[12:13], 11
	s_lshl_b32 s20, s18, 7
	v_lshl_add_u64 v[0:1], s[12:13], 0, v[22:23]
	v_or_b32_e32 v2, s20, v27
	v_lshlrev_b64 v[0:1], 11, v[0:1]
	v_lshl_or_b32 v0, v2, 1, v0
	v_lshl_add_u64 v[0:1], v[0:1], 0, s[10:11]
	v_lshl_add_u64 v[2:3], s[28:29], 0, v[0:1]
	v_lshl_add_u64 v[6:7], v[2:3], 0, s[22:23]
	v_add_co_u32_e32 v2, vcc, s21, v2
	v_lshl_add_u64 v[4:5], s[30:31], 0, v[0:1]
	s_nop 0
	v_addc_co_u32_e32 v3, vcc, 0, v3, vcc
	v_lshl_add_u64 v[8:9], v[4:5], 0, s[24:25]
	v_add_co_u32_e32 v4, vcc, s38, v4
	v_lshl_add_u64 v[0:1], s[34:35], 0, v[0:1]
	s_nop 0
	v_addc_co_u32_e32 v5, vcc, 0, v5, vcc
	v_lshl_add_u64 v[10:11], v[0:1], 0, s[26:27]
	v_add_co_u32_e32 v0, vcc, s39, v0
	s_ashr_i32 s3, s2, 31
	s_nop 0
	v_addc_co_u32_e32 v1, vcc, 0, v1, vcc
	global_load_dwordx4 v[48:51], v[2:3], off
	global_load_dwordx4 v[44:47], v[6:7], off offset:16
	global_load_dwordx4 v[36:39], v[4:5], off
	global_load_dwordx4 v[28:31], v[8:9], off offset:16
	global_load_dwordx4 v[16:19], v[0:1], off
	global_load_dwordx4 v[12:15], v[10:11], off offset:16
	s_load_dwordx2 s[10:11], s[0:1], 0x108
	s_lshl_b32 s14, s18, 8
	s_lshl_b64 s[18:19], s[2:3], 11
	s_lshl_b64 s[12:13], s[2:3], 17
	s_or_b32 s18, s18, 64
	v_lshl_add_u64 v[0:1], s[18:19], 0, v[22:23]
	s_waitcnt lgkmcnt(0)
	s_add_u32 s10, s10, 0x2880000
	v_lshlrev_b64 v[0:1], 2, v[0:1]
	s_addc_u32 s11, s11, 0
	s_lshl_b64 s[18:19], s[18:19], 2
	v_lshl_add_u64 v[2:3], s[10:11], 0, v[0:1]
	s_add_u32 s10, s10, s18
	s_addc_u32 s11, s11, s19
	global_load_dword v123, v[2:3], off
	global_load_dword v124, v21, s[10:11] offset:124
	s_load_dwordx2 s[10:11], s[0:1], 0x108
	s_mov_b32 s28, 0x2f10000
	v_lshl_add_u64 v[2:3], s[36:37], 0, v[24:25]
	v_lshl_add_u64 v[2:3], v[2:3], 0, s[14:15]
	s_mov_b32 s29, 0x8a68000
	s_waitcnt lgkmcnt(0)
	v_lshl_add_u64 v[4:5], s[10:11], 0, v[0:1]
	v_add_co_u32_e32 v4, vcc, s28, v4
	s_mov_b32 s30, 0x8ae8000
	s_nop 0
	v_addc_co_u32_e32 v5, vcc, 0, v5, vcc
	global_load_dword v116, v[4:5], off
	s_load_dwordx2 s[10:11], s[0:1], 0x100
	v_lshl_add_u64 v[4:5], v[2:3], 0, v[114:115]
	s_mov_b64 s[18:19], 0xf180000
	v_lshl_add_u64 v[108:109], v[4:5], 0, s[18:19]
	s_movk_i32 s21, 0x180
	s_waitcnt lgkmcnt(0)
	v_lshl_add_u64 v[2:3], s[10:11], 0, v[0:1]
	v_add_co_u32_e32 v2, vcc, s29, v2
	s_mov_b32 s31, 0xf180000
	s_nop 0
	v_addc_co_u32_e32 v3, vcc, 0, v3, vcc
	global_load_dword v125, v[2:3], off
	s_load_dwordx2 s[10:11], s[0:1], 0x100
	v_and_b32_e32 v2, 0x7f0, v32
	v_mov_b32_e32 v3, v21
	v_lshlrev_b32_e32 v32, 3, v26
	v_and_b32_e32 v32, 24, v32
	s_waitcnt lgkmcnt(0)
	v_lshl_add_u64 v[0:1], s[10:11], 0, v[0:1]
	v_add_co_u32_e32 v0, vcc, s30, v0
	v_cmp_gt_i32_e64 s[10:11], s21, v26
	s_nop 0
	v_addc_co_u32_e32 v1, vcc, 0, v1, vcc
	global_load_dword v126, v[0:1], off
	s_load_dwordx2 s[18:19], s[0:1], 0x108
	v_mov_b32_e32 v0, 0x1980000
	v_mov_b32_e32 v1, 0x1180000
	v_cndmask_b32_e64 v20, v0, v1, s[10:11]
	v_cndmask_b32_e64 v115, v34, v35, s[10:11]
	s_waitcnt lgkmcnt(0)
	v_lshl_add_u64 v[0:1], s[18:19], 0, v[20:21]
	v_lshl_add_u64 v[0:1], v[0:1], 0, s[12:13]
	v_lshl_add_u64 v[0:1], v[0:1], 0, v[2:3]
	s_movk_i32 s18, 0x1000
	v_add_co_u32_e32 v0, vcc, s18, v0
	v_bfe_u32 v34, v26, 2, 5
	s_nop 0
	v_addc_co_u32_e32 v1, vcc, 0, v1, vcc
	v_add_co_u32_e32 v4, vcc, 0xf180000, v4
	global_load_dwordx4 v[0:3], v[0:1], off
	s_nop 0
	v_addc_co_u32_e32 v5, vcc, 0, v5, vcc
	global_load_dwordx4 v[8:11], v[4:5], off
	s_nop 0
	global_load_dwordx4 v[4:7], v[108:109], off offset:16
	v_mul_u32_u24_e32 v121, 0x50, v34
	v_cmp_eq_u32_e64 s[10:11], 0, v33
	v_add_u32_e32 v33, 0, v115
	v_lshlrev_b32_e32 v122, 1, v32
	v_add3_u32 v32, v33, v121, v122
	s_waitcnt vmcnt(30)
	ds_write_b128 v32, v[88:91] offset:49680
	s_and_saveexec_b64 s[18:19], s[10:11]
	s_cbranch_execz .LBB0_1837
	v_mul_f32_e32 v32, 0x3fb8aa3b, v118
	v_exp_f32_e32 v32, v32
	s_add_i32 s21, 0, 0x18410
	v_mov_b32_e32 v33, s21
	ds_write_b32 v33, v32
